# HGRN pass C: key-side decay operand and q*exp(b) operand computed once per unit into LDS (static LDS +21760) instead of per block / per wave
# speedup vs baseline: 1.0053x; 1.0053x over previous
.LBB0_312:
	s_or_b64 exec, exec, s[4:5]
	v_add_f32_e32 v150, v0, v121
	v_add_f32_e32 v151, v122, v121
	v_add_f32_e32 v152, v119, v121
	v_add_f32_e32 v153, v120, v121
	v_add_f32_e32 v154, v117, v121
	v_add_f32_e32 v155, v118, v121
	v_add_f32_e32 v156, v115, v121
	v_add_f32_e32 v157, v116, v121
	v_add_f32_e32 v158, v14, v121
	v_add_f32_e32 v159, v15, v121
	v_add_f32_e32 v160, v12, v121
	v_add_f32_e32 v161, v13, v121
	v_add_f32_e32 v162, v10, v121
	v_add_f32_e32 v163, v11, v121
	v_add_f32_e32 v164, v1, v121
	v_add_f32_e32 v165, v9, v121
	v_lshrrev_b32_e32 v166, 1, v114
	v_lshl_add_u32 v166, v84, 7, v166
	v_mov_b32_e32 v188, 0x3fb8aa3b
	v_mov_b32_e32 v167, 0x1cc00
	v_mov_b32_e32 v168, 0x1d100
	v_cmp_eq_u32_e32 vcc, 3, v84
	s_nop 0
	v_cndmask_b32_e32 v167, v167, v168, vcc
	v_add_u32_e32 v167, v167, v166
	v_add_u32_e32 v168, 0x21500, v166
	ds_read_u16 v170, v166 offset:35840
	ds_read_u16 v171, v166 offset:36112
	ds_read_u16 v172, v166 offset:36384
	ds_read_u16 v173, v166 offset:36656
	ds_read_u16 v174, v166 offset:36928
	ds_read_u16 v175, v166 offset:37200
	ds_read_u16 v176, v166 offset:37472
	ds_read_u16 v177, v166 offset:37744
	v_sub_f32_e32 v190, v150, v121
	v_sub_f32_e32 v191, v151, v150
	v_pk_add_f32 v[198:199], v[164:165], v[150:151] op_sel:[1,0] op_sel_hi:[1,1] neg_lo:[0,1] neg_hi:[0,1]
	v_sub_f32_e32 v192, v152, v151
	v_sub_f32_e32 v193, v153, v152
	v_pk_add_f32 v[200:201], v[164:165], v[152:153] op_sel:[1,0] op_sel_hi:[1,1] neg_lo:[0,1] neg_hi:[0,1]
	v_sub_f32_e32 v194, v154, v153
	v_sub_f32_e32 v195, v155, v154
	v_pk_add_f32 v[202:203], v[164:165], v[154:155] op_sel:[1,0] op_sel_hi:[1,1] neg_lo:[0,1] neg_hi:[0,1]
	v_sub_f32_e32 v196, v156, v155
	v_sub_f32_e32 v197, v157, v156
	v_pk_add_f32 v[204:205], v[164:165], v[156:157] op_sel:[1,0] op_sel_hi:[1,1] neg_lo:[0,1] neg_hi:[0,1]
	v_pk_mul_f32 v[190:191], v[190:191], v[188:189] op_sel_hi:[1,0]
	v_pk_mul_f32 v[198:199], v[198:199], v[188:189] op_sel_hi:[1,0]
	v_pk_mul_f32 v[192:193], v[192:193], v[188:189] op_sel_hi:[1,0]
	v_pk_mul_f32 v[200:201], v[200:201], v[188:189] op_sel_hi:[1,0]
	v_pk_mul_f32 v[194:195], v[194:195], v[188:189] op_sel_hi:[1,0]
	v_pk_mul_f32 v[202:203], v[202:203], v[188:189] op_sel_hi:[1,0]
	v_pk_mul_f32 v[196:197], v[196:197], v[188:189] op_sel_hi:[1,0]
	v_pk_mul_f32 v[204:205], v[204:205], v[188:189] op_sel_hi:[1,0]
	v_exp_f32_e32 v190, v190
	v_exp_f32_e32 v191, v191
	v_exp_f32_e32 v198, v198
	v_exp_f32_e32 v199, v199
	v_exp_f32_e32 v192, v192
	v_exp_f32_e32 v193, v193
	v_exp_f32_e32 v200, v200
	v_exp_f32_e32 v201, v201
	v_exp_f32_e32 v194, v194
	v_exp_f32_e32 v195, v195
	v_exp_f32_e32 v202, v202
	v_exp_f32_e32 v203, v203
	v_exp_f32_e32 v196, v196
	v_exp_f32_e32 v197, v197
	v_exp_f32_e32 v204, v204
	v_exp_f32_e32 v205, v205
	s_nop 0
	v_pk_add_f32 v[190:191], v[190:191], 1.0 op_sel_hi:[1,0] neg_lo:[1,0] neg_hi:[1,0]
	v_pk_add_f32 v[192:193], v[192:193], 1.0 op_sel_hi:[1,0] neg_lo:[1,0] neg_hi:[1,0]
	v_pk_add_f32 v[194:195], v[194:195], 1.0 op_sel_hi:[1,0] neg_lo:[1,0] neg_hi:[1,0]
	v_pk_add_f32 v[196:197], v[196:197], 1.0 op_sel_hi:[1,0] neg_lo:[1,0] neg_hi:[1,0]
	v_pk_mul_f32 v[190:191], v[198:199], v[190:191]
	v_pk_mul_f32 v[192:193], v[200:201], v[192:193]
	v_pk_mul_f32 v[194:195], v[202:203], v[194:195]
	v_pk_mul_f32 v[196:197], v[204:205], v[196:197]
	v_cvt_pk_bf16_f32 v190, v190, v191
	v_cvt_pk_bf16_f32 v192, v192, v193
	v_cvt_pk_bf16_f32 v194, v194, v195
	v_cvt_pk_bf16_f32 v196, v196, v197
	s_waitcnt lgkmcnt(7)
	ds_write_b16 v168, v190 offset:0
	ds_write_b16_d16_hi v168, v190 offset:272
	ds_write_b16 v168, v192 offset:544
	ds_write_b16_d16_hi v168, v192 offset:816
	ds_write_b16 v168, v194 offset:1088
	ds_write_b16_d16_hi v168, v194 offset:1360
	ds_write_b16 v168, v196 offset:1632
	ds_write_b16_d16_hi v168, v196 offset:1904
	v_pk_mul_f32 v[190:191], v[150:151], v[188:189] op_sel_hi:[1,0]
	v_pk_mul_f32 v[192:193], v[152:153], v[188:189] op_sel_hi:[1,0]
	v_pk_mul_f32 v[194:195], v[154:155], v[188:189] op_sel_hi:[1,0]
	v_pk_mul_f32 v[196:197], v[156:157], v[188:189] op_sel_hi:[1,0]
	v_exp_f32_e32 v190, v190
	v_exp_f32_e32 v191, v191
	v_exp_f32_e32 v192, v192
	v_exp_f32_e32 v193, v193
	v_exp_f32_e32 v194, v194
	v_exp_f32_e32 v195, v195
	v_exp_f32_e32 v196, v196
	v_exp_f32_e32 v197, v197
	s_waitcnt lgkmcnt(8)
	v_lshlrev_b32_e32 v170, 16, v170
	v_lshlrev_b32_e32 v171, 16, v171
	v_lshlrev_b32_e32 v172, 16, v172
	v_lshlrev_b32_e32 v173, 16, v173
	v_lshlrev_b32_e32 v174, 16, v174
	v_lshlrev_b32_e32 v175, 16, v175
	v_lshlrev_b32_e32 v176, 16, v176
	v_lshlrev_b32_e32 v177, 16, v177
	v_pk_mul_f32 v[190:191], v[190:191], v[170:171]
	v_pk_mul_f32 v[192:193], v[192:193], v[172:173]
	v_pk_mul_f32 v[194:195], v[194:195], v[174:175]
	v_pk_mul_f32 v[196:197], v[196:197], v[176:177]
	v_cvt_pk_bf16_f32 v190, v190, v191
	v_cvt_pk_bf16_f32 v192, v192, v193
	v_cvt_pk_bf16_f32 v194, v194, v195
	v_cvt_pk_bf16_f32 v196, v196, v197
	s_waitcnt lgkmcnt(7)
	ds_write_b16 v167, v190 offset:0
	ds_write_b16_d16_hi v167, v190 offset:272
	ds_write_b16 v167, v192 offset:544
	ds_write_b16_d16_hi v167, v192 offset:816
	ds_write_b16 v167, v194 offset:1088
	ds_write_b16_d16_hi v167, v194 offset:1360
	ds_write_b16 v167, v196 offset:1632
	ds_write_b16_d16_hi v167, v196 offset:1904
	s_waitcnt lgkmcnt(7)
	ds_read_u16 v178, v166 offset:38016
	ds_read_u16 v179, v166 offset:38288
	ds_read_u16 v180, v166 offset:38560
	ds_read_u16 v181, v166 offset:38832
	ds_read_u16 v182, v166 offset:39104
	ds_read_u16 v183, v166 offset:39376
	ds_read_u16 v184, v166 offset:39648
	ds_read_u16 v185, v166 offset:39920
	v_sub_f32_e32 v190, v158, v157
	v_sub_f32_e32 v191, v159, v158
	v_pk_add_f32 v[198:199], v[164:165], v[158:159] op_sel:[1,0] op_sel_hi:[1,1] neg_lo:[0,1] neg_hi:[0,1]
	v_sub_f32_e32 v192, v160, v159
	v_sub_f32_e32 v193, v161, v160
	v_pk_add_f32 v[200:201], v[164:165], v[160:161] op_sel:[1,0] op_sel_hi:[1,1] neg_lo:[0,1] neg_hi:[0,1]
	v_sub_f32_e32 v194, v162, v161
	v_sub_f32_e32 v195, v163, v162
	v_pk_add_f32 v[202:203], v[164:165], v[162:163] op_sel:[1,0] op_sel_hi:[1,1] neg_lo:[0,1] neg_hi:[0,1]
	v_sub_f32_e32 v196, v164, v163
	v_sub_f32_e32 v197, v165, v164
	v_pk_add_f32 v[204:205], v[164:165], v[164:165] op_sel:[1,0] op_sel_hi:[1,1] neg_lo:[0,1] neg_hi:[0,1]
	v_pk_mul_f32 v[190:191], v[190:191], v[188:189] op_sel_hi:[1,0]
	v_pk_mul_f32 v[198:199], v[198:199], v[188:189] op_sel_hi:[1,0]
	v_pk_mul_f32 v[192:193], v[192:193], v[188:189] op_sel_hi:[1,0]
	v_pk_mul_f32 v[200:201], v[200:201], v[188:189] op_sel_hi:[1,0]
	v_pk_mul_f32 v[194:195], v[194:195], v[188:189] op_sel_hi:[1,0]
	v_pk_mul_f32 v[202:203], v[202:203], v[188:189] op_sel_hi:[1,0]
	v_pk_mul_f32 v[196:197], v[196:197], v[188:189] op_sel_hi:[1,0]
	v_pk_mul_f32 v[204:205], v[204:205], v[188:189] op_sel_hi:[1,0]
	v_exp_f32_e32 v190, v190
	v_exp_f32_e32 v191, v191
	v_exp_f32_e32 v198, v198
	v_exp_f32_e32 v199, v199
	v_exp_f32_e32 v192, v192
	v_exp_f32_e32 v193, v193
	v_exp_f32_e32 v200, v200
	v_exp_f32_e32 v201, v201
	v_exp_f32_e32 v194, v194
	v_exp_f32_e32 v195, v195
	v_exp_f32_e32 v202, v202
	v_exp_f32_e32 v203, v203
	v_exp_f32_e32 v196, v196
	v_exp_f32_e32 v197, v197
	v_exp_f32_e32 v204, v204
	v_exp_f32_e32 v205, v205
	s_nop 0
	v_pk_add_f32 v[190:191], v[190:191], 1.0 op_sel_hi:[1,0] neg_lo:[1,0] neg_hi:[1,0]
	v_pk_add_f32 v[192:193], v[192:193], 1.0 op_sel_hi:[1,0] neg_lo:[1,0] neg_hi:[1,0]
	v_pk_add_f32 v[194:195], v[194:195], 1.0 op_sel_hi:[1,0] neg_lo:[1,0] neg_hi:[1,0]
	v_pk_add_f32 v[196:197], v[196:197], 1.0 op_sel_hi:[1,0] neg_lo:[1,0] neg_hi:[1,0]
	v_pk_mul_f32 v[190:191], v[198:199], v[190:191]
	v_pk_mul_f32 v[192:193], v[200:201], v[192:193]
	v_pk_mul_f32 v[194:195], v[202:203], v[194:195]
	v_pk_mul_f32 v[196:197], v[204:205], v[196:197]
	v_cvt_pk_bf16_f32 v190, v190, v191
	v_cvt_pk_bf16_f32 v192, v192, v193
	v_cvt_pk_bf16_f32 v194, v194, v195
	v_cvt_pk_bf16_f32 v196, v196, v197
	s_waitcnt lgkmcnt(7)
	ds_write_b16 v168, v190 offset:2176
	ds_write_b16_d16_hi v168, v190 offset:2448
	ds_write_b16 v168, v192 offset:2720
	ds_write_b16_d16_hi v168, v192 offset:2992
	ds_write_b16 v168, v194 offset:3264
	ds_write_b16_d16_hi v168, v194 offset:3536
	ds_write_b16 v168, v196 offset:3808
	ds_write_b16_d16_hi v168, v196 offset:4080
	v_pk_mul_f32 v[190:191], v[158:159], v[188:189] op_sel_hi:[1,0]
	v_pk_mul_f32 v[192:193], v[160:161], v[188:189] op_sel_hi:[1,0]
	v_pk_mul_f32 v[194:195], v[162:163], v[188:189] op_sel_hi:[1,0]
	v_pk_mul_f32 v[196:197], v[164:165], v[188:189] op_sel_hi:[1,0]
	v_exp_f32_e32 v190, v190
	v_exp_f32_e32 v191, v191
	v_exp_f32_e32 v192, v192
	v_exp_f32_e32 v193, v193
	v_exp_f32_e32 v194, v194
	v_exp_f32_e32 v195, v195
	v_exp_f32_e32 v196, v196
	v_exp_f32_e32 v197, v197
	s_waitcnt lgkmcnt(8)
	v_lshlrev_b32_e32 v178, 16, v178
	v_lshlrev_b32_e32 v179, 16, v179
	v_lshlrev_b32_e32 v180, 16, v180
	v_lshlrev_b32_e32 v181, 16, v181
	v_lshlrev_b32_e32 v182, 16, v182
	v_lshlrev_b32_e32 v183, 16, v183
	v_lshlrev_b32_e32 v184, 16, v184
	v_lshlrev_b32_e32 v185, 16, v185
	v_pk_mul_f32 v[190:191], v[190:191], v[178:179]
	v_pk_mul_f32 v[192:193], v[192:193], v[180:181]
	v_pk_mul_f32 v[194:195], v[194:195], v[182:183]
	v_pk_mul_f32 v[196:197], v[196:197], v[184:185]
	v_cvt_pk_bf16_f32 v190, v190, v191
	v_cvt_pk_bf16_f32 v192, v192, v193
	v_cvt_pk_bf16_f32 v194, v194, v195
	v_cvt_pk_bf16_f32 v196, v196, v197
	s_waitcnt lgkmcnt(7)
	ds_write_b16 v167, v190 offset:2176
	ds_write_b16_d16_hi v167, v190 offset:2448
	ds_write_b16 v167, v192 offset:2720
	ds_write_b16_d16_hi v167, v192 offset:2992
	ds_write_b16 v167, v194 offset:3264
	ds_write_b16_d16_hi v167, v194 offset:3536
	ds_write_b16 v167, v196 offset:3808
	ds_write_b16_d16_hi v167, v196 offset:4080
	s_waitcnt lgkmcnt(7)
	v_add_f32_e32 v0, v0, v121
	v_add_f32_e32 v122, v122, v121
	ds_write2_b32 v114, v0, v122 offset1:132
	v_add_f32_e32 v0, v119, v121
	v_add_f32_e32 v119, v120, v121
	ds_write2_b32 v8, v0, v119 offset0:8 offset1:140
	v_add_f32_e32 v0, v117, v121
	v_add_f32_e32 v8, v118, v121
	ds_write2_b32 v7, v0, v8 offset0:16 offset1:148
	v_add_f32_e32 v0, v115, v121
	v_add_f32_e32 v7, v116, v121
	ds_write2_b32 v6, v0, v7 offset0:24 offset1:156
	v_add_f32_e32 v0, v14, v121
	v_add_f32_e32 v6, v15, v121
	ds_write2_b32 v5, v0, v6 offset0:32 offset1:164
	v_add_f32_e32 v0, v12, v121
	v_add_f32_e32 v5, v13, v121
	ds_write2_b32 v4, v0, v5 offset0:40 offset1:172
	v_add_f32_e32 v0, v10, v121
	v_add_f32_e32 v4, v11, v121
	ds_write2_b32 v3, v0, v4 offset0:48 offset1:180
	v_add_f32_e32 v0, v1, v121
	v_add_f32_e32 v1, v9, v121
	s_andn2_b64 vcc, exec, s[34:35]
	s_mov_b32 s4, s60
	s_mov_b32 s5, s56
	ds_write2_b32 v2, v0, v1 offset0:56 offset1:188
	s_waitcnt lgkmcnt(0)
	s_barrier
	s_cbranch_vccz .LBB0_324
.LBB0_313:
	v_mov_b32_e32 v151, 0x1cc00
	v_mov_b32_e32 v152, 0x1d100
	v_cmp_lt_u32_e32 vcc, 0x32ff, v94
	s_add_i32 s61, s61, s6
	v_cndmask_b32_e32 v151, v151, v152, vcc
	v_add_u32_e32 v150, v94, v151
	ds_read_b128 v[116:119], v150
	ds_read_b128 v[120:123], v95
	ds_read_b128 v[124:127], v150 offset:32
	ds_read_b128 v[128:131], v95 offset:32
	ds_read_b128 v[132:135], v150 offset:64
	ds_read_b128 v[136:139], v95 offset:64
	ds_read_b128 v[140:143], v150 offset:96
	ds_read_b128 v[144:147], v95 offset:96
	ds_read_b128 v[152:155], v150 offset:128
	ds_read_b128 v[156:159], v95 offset:128
	ds_read_b128 v[160:163], v150 offset:160
	ds_read_b128 v[164:167], v95 offset:160
	ds_read_b128 v[168:171], v150 offset:192
	ds_read_b128 v[172:175], v95 offset:192
	s_cmpk_lt_i32 s61, 0x800
	s_cselect_b64 s[4:5], -1, 0
	s_cmpk_gt_i32 s61, 0x7ff
	s_cselect_b64 s[48:49], -1, 0
	s_and_b64 vcc, exec, s[4:5]
	s_waitcnt lgkmcnt(12)
	v_mfma_f32_32x32x16_bf16 v[0:15], v[116:119], v[120:123], 0
	ds_read_b128 v[176:179], v150 offset:224
	ds_read_b128 v[180:183], v95 offset:224
	s_waitcnt lgkmcnt(12)
	v_mfma_f32_32x32x16_bf16 v[0:15], v[124:127], v[128:131], v[0:15]
	s_waitcnt lgkmcnt(10)
	v_mfma_f32_32x32x16_bf16 v[0:15], v[132:135], v[136:139], v[0:15]
	s_waitcnt lgkmcnt(8)
	v_mfma_f32_32x32x16_bf16 v[0:15], v[140:143], v[144:147], v[0:15]
	s_waitcnt lgkmcnt(6)
	v_mfma_f32_32x32x16_bf16 v[0:15], v[152:155], v[156:159], v[0:15]
	s_waitcnt lgkmcnt(4)
	v_mfma_f32_32x32x16_bf16 v[0:15], v[160:163], v[164:167], v[0:15]
	s_waitcnt lgkmcnt(2)
	v_mfma_f32_32x32x16_bf16 v[0:15], v[168:171], v[172:175], v[0:15]
	s_waitcnt lgkmcnt(0)
	v_mfma_f32_32x32x16_bf16 v[0:15], v[176:179], v[180:183], v[0:15]
	s_barrier
	ds_read_b64_tr_b16 v[116:117], v96 offset:53248
	ds_read_b64_tr_b16 v[118:119], v96 offset:54528
	ds_read_b128 v[120:123], v90
	ds_read_b128 v[124:127], v90 offset:32
	s_waitcnt lgkmcnt(1)
	v_mfma_f32_32x32x16_bf16 v[0:15], v[120:123], v[116:119], v[0:15]
	ds_read_b64_tr_b16 v[116:117], v96 offset:58368
	ds_read_b64_tr_b16 v[118:119], v96 offset:59648
	s_waitcnt lgkmcnt(0)
	v_mfma_f32_32x32x16_bf16 v[0:15], v[124:127], v[116:119], v[0:15]
	ds_read_b128 v[116:119], v90 offset:64
	ds_read_b64_tr_b16 v[120:121], v96 offset:63488
	ds_read_b64_tr_b16 v[122:123], v96 offset:64768
	s_waitcnt lgkmcnt(0)
	v_mfma_f32_32x32x16_bf16 v[0:15], v[116:119], v[120:123], v[0:15]
	ds_read_b128 v[116:119], v90 offset:96
	ds_read_b64_tr_b16 v[120:121], v97 offset:15360
	ds_read_b64_tr_b16 v[122:123], v97 offset:16640
	s_waitcnt lgkmcnt(0)
	v_mfma_f32_32x32x16_bf16 v[0:15], v[116:119], v[120:123], v[0:15]
	s_nop 11
	ds_write2_b32 v107, v0, v1 offset1:132
	v_add_u32_e32 v0, 0x400, v107
	ds_write2_b32 v0, v2, v3 offset0:8 offset1:140
	v_add_u32_e32 v0, 0x1000, v107
	ds_write2_b32 v0, v4, v5 offset0:32 offset1:164
	v_add_u32_e32 v0, 0x1400, v107
	ds_write2_b32 v0, v6, v7 offset0:40 offset1:172
	v_add_u32_e32 v0, 0x2000, v107
	ds_write2_b32 v0, v8, v9 offset0:64 offset1:196
	v_add_u32_e32 v0, 0x2400, v107
	ds_write2_b32 v0, v10, v11 offset0:72 offset1:204
	v_add_u32_e32 v0, 0x3000, v107
	ds_write2_b32 v0, v12, v13 offset0:96 offset1:228
	v_add_u32_e32 v0, 0x3400, v107
	ds_write2_b32 v0, v14, v15 offset0:104 offset1:236
	s_waitcnt lgkmcnt(0)
	s_barrier
	s_cbranch_vccz .LBB0_318
	s_waitcnt vmcnt(11)
	v_cvt_f32_f16_sdwa v1, v16 dst_sel:DWORD dst_unused:UNUSED_PAD src0_sel:WORD_1
	v_cvt_f32_f16_e32 v0, v16
	v_cvt_f32_f16_sdwa v3, v17 dst_sel:DWORD dst_unused:UNUSED_PAD src0_sel:WORD_1
	v_cvt_f32_f16_e32 v2, v17
	ds_write_b128 v108, v[0:3]
	v_cvt_f32_f16_sdwa v1, v18 dst_sel:DWORD dst_unused:UNUSED_PAD src0_sel:WORD_1
	v_cvt_f32_f16_e32 v0, v18
	v_cvt_f32_f16_sdwa v3, v19 dst_sel:DWORD dst_unused:UNUSED_PAD src0_sel:WORD_1
	v_cvt_f32_f16_e32 v2, v19
	ds_write_b128 v108, v[0:3] offset:16
	s_waitcnt vmcnt(10)
	ds_write_b128 v109, v[20:23] offset:53248
	v_add_u32_e32 v0, v91, v99
	s_waitcnt vmcnt(9)
	ds_write_b128 v0, v[24:27] offset:35840
	s_waitcnt vmcnt(8)
	v_cvt_f32_f16_sdwa v1, v28 dst_sel:DWORD dst_unused:UNUSED_PAD src0_sel:WORD_1
	v_cvt_f32_f16_e32 v0, v28
	v_cvt_f32_f16_sdwa v3, v29 dst_sel:DWORD dst_unused:UNUSED_PAD src0_sel:WORD_1
	v_cvt_f32_f16_e32 v2, v29
	ds_write_b128 v110, v[0:3]
	v_cvt_f32_f16_sdwa v1, v30 dst_sel:DWORD dst_unused:UNUSED_PAD src0_sel:WORD_1
	v_cvt_f32_f16_e32 v0, v30
	v_cvt_f32_f16_sdwa v3, v31 dst_sel:DWORD dst_unused:UNUSED_PAD src0_sel:WORD_1
	v_cvt_f32_f16_e32 v2, v31
	ds_write_b128 v110, v[0:3] offset:16
	s_waitcnt vmcnt(7)
	ds_write_b128 v111, v[32:35] offset:53248
	v_add_u32_e32 v0, v91, v101
	s_waitcnt vmcnt(6)
	ds_write_b128 v0, v[36:39] offset:35840
	v_mov_b32_e32 v0, 0
	s_and_saveexec_b64 s[36:37], s[10:11]
	s_cbranch_execz .LBB0_317
	v_mov_b32_e32 v1, v0
	v_mov_b32_e32 v2, v0
	v_mov_b32_e32 v3, v0
	s_mov_b64 s[58:59], 0
	v_mov_b32_e32 v4, v106
	v_mov_b32_e32 v5, v105

.LBB0_323:
	s_lshl_b32 s37, s36, 4
	s_mul_i32 s28, s33, 0x2100
	v_or_b32_e32 v0, s37, v86
	v_mul_lo_u32 v1, v0, s42
	v_lshlrev_b32_e32 v0, 8, v0
	v_add_u32_e32 v5, s28, v103
	v_lshl_or_b32 v6, s33, 4, v86
	v_sub_u32_e32 v9, v1, v0
	v_lshl_add_u32 v4, v87, 2, v1
	v_lshlrev_b32_e32 v7, 8, v6
	v_lshl_add_u32 v8, v87, 1, v9
	v_lshl_add_u32 v7, v6, 4, v7
	v_lshl_add_u32 v7, v87, 1, v7
	v_add_u32_e32 v7, 0x21500, v7
	v_mov_b32_e32 v148, 0x3fb8aa3b
	ds_read_b128 v[10:13], v5 offset:7920
	ds_read_b128 v[116:119], v5 offset:7936
	ds_read_b128 v[120:123], v4
	ds_read_b128 v[124:127], v4 offset:16
	ds_read_b128 v[128:131], v8 offset:35840
	ds_read_b128 v[132:135], v7
	s_cmp_eq_u32 s36, s33
	s_cselect_b64 s[48:49], -1, 0
	s_movk_i32 s29, 0x90
	s_add_i32 s5, s5, 8
	s_add_i32 s4, s4, 8
	s_waitcnt lgkmcnt(2)
	v_sub_f32_e32 v140, v120, v10
	v_sub_f32_e32 v141, v121, v11
	v_sub_f32_e32 v142, v122, v12
	v_sub_f32_e32 v143, v123, v13
	v_sub_f32_e32 v144, v124, v116
	v_sub_f32_e32 v145, v125, v117
	v_sub_f32_e32 v146, v126, v118
	v_sub_f32_e32 v147, v127, v119
	ds_read_b128 v[10:13], v5 offset:8048
	ds_read_b128 v[116:119], v5 offset:8064
	ds_read_b128 v[120:123], v4 offset:128
	ds_read_b128 v[124:127], v4 offset:144
	v_pk_mul_f32 v[140:141], v[140:141], v[148:149] op_sel_hi:[1,0]
	v_pk_mul_f32 v[142:143], v[142:143], v[148:149] op_sel_hi:[1,0]
	v_pk_mul_f32 v[144:145], v[144:145], v[148:149] op_sel_hi:[1,0]
	v_pk_mul_f32 v[146:147], v[146:147], v[148:149] op_sel_hi:[1,0]
	v_exp_f32_e32 v140, v140
	v_exp_f32_e32 v141, v141
	v_exp_f32_e32 v142, v142
	v_exp_f32_e32 v143, v143
	v_exp_f32_e32 v144, v144
	v_exp_f32_e32 v145, v145
	v_exp_f32_e32 v146, v146
	v_exp_f32_e32 v147, v147
	s_waitcnt lgkmcnt(5)
	v_lshlrev_b32_e32 v150, 16, v128
	v_and_b32_e32 v151, 0xffff0000, v128
	v_lshlrev_b32_e32 v152, 16, v129
	v_and_b32_e32 v153, 0xffff0000, v129
	v_lshlrev_b32_e32 v154, 16, v130
	v_and_b32_e32 v155, 0xffff0000, v130
	v_lshlrev_b32_e32 v156, 16, v131
	v_and_b32_e32 v157, 0xffff0000, v131
	ds_read_b128 v[128:131], v8 offset:35904
	ds_read_b128 v[136:139], v7 offset:64
	v_pk_mul_f32 v[140:141], v[140:141], v[150:151]
	v_pk_mul_f32 v[142:143], v[142:143], v[152:153]
	v_pk_mul_f32 v[144:145], v[144:145], v[154:155]
	v_pk_mul_f32 v[146:147], v[146:147], v[156:157]
	v_cvt_pk_bf16_f32 v160, v140, v141
	v_cvt_pk_bf16_f32 v161, v142, v143
	v_cvt_pk_bf16_f32 v162, v144, v145
	v_cvt_pk_bf16_f32 v163, v146, v147
	s_waitcnt lgkmcnt(6)
	s_nop 1
	v_mfma_f32_16x16x32_bf16 v[0:3], v[160:163], v[132:135], 0
	s_waitcnt lgkmcnt(2)
	v_sub_f32_e32 v140, v120, v10
	v_sub_f32_e32 v141, v121, v11
	v_sub_f32_e32 v142, v122, v12
	v_sub_f32_e32 v143, v123, v13
	v_sub_f32_e32 v144, v124, v116
	v_sub_f32_e32 v145, v125, v117
	v_sub_f32_e32 v146, v126, v118
	v_sub_f32_e32 v147, v127, v119
	ds_read_b128 v[10:13], v5 offset:8176
	ds_read_b128 v[116:119], v5 offset:8192
	ds_read_b128 v[120:123], v4 offset:256
	ds_read_b128 v[124:127], v4 offset:272
	v_pk_mul_f32 v[140:141], v[140:141], v[148:149] op_sel_hi:[1,0]
	v_pk_mul_f32 v[142:143], v[142:143], v[148:149] op_sel_hi:[1,0]
	v_pk_mul_f32 v[144:145], v[144:145], v[148:149] op_sel_hi:[1,0]
	v_pk_mul_f32 v[146:147], v[146:147], v[148:149] op_sel_hi:[1,0]
	v_exp_f32_e32 v140, v140
	v_exp_f32_e32 v141, v141
	v_exp_f32_e32 v142, v142
	v_exp_f32_e32 v143, v143
	v_exp_f32_e32 v144, v144
	v_exp_f32_e32 v145, v145
	v_exp_f32_e32 v146, v146
	v_exp_f32_e32 v147, v147
	s_waitcnt lgkmcnt(5)
	v_lshlrev_b32_e32 v150, 16, v128
	v_and_b32_e32 v151, 0xffff0000, v128
	v_lshlrev_b32_e32 v152, 16, v129
	v_and_b32_e32 v153, 0xffff0000, v129
	v_lshlrev_b32_e32 v154, 16, v130
	v_and_b32_e32 v155, 0xffff0000, v130
	v_lshlrev_b32_e32 v156, 16, v131
	v_and_b32_e32 v157, 0xffff0000, v131
	ds_read_b128 v[128:131], v8 offset:35968
	ds_read_b128 v[132:135], v7 offset:128
	v_pk_mul_f32 v[140:141], v[140:141], v[150:151]
	v_pk_mul_f32 v[142:143], v[142:143], v[152:153]
	v_pk_mul_f32 v[144:145], v[144:145], v[154:155]
	v_pk_mul_f32 v[146:147], v[146:147], v[156:157]
	v_cvt_pk_bf16_f32 v160, v140, v141
	v_cvt_pk_bf16_f32 v161, v142, v143
	v_cvt_pk_bf16_f32 v162, v144, v145
	v_cvt_pk_bf16_f32 v163, v146, v147
	s_waitcnt lgkmcnt(6)
	s_nop 1
	v_mfma_f32_16x16x32_bf16 v[0:3], v[160:163], v[136:139], v[0:3]
	s_waitcnt lgkmcnt(2)
	v_sub_f32_e32 v140, v120, v10
	v_sub_f32_e32 v141, v121, v11
	v_sub_f32_e32 v142, v122, v12
	v_sub_f32_e32 v143, v123, v13
	v_sub_f32_e32 v144, v124, v116
	v_sub_f32_e32 v145, v125, v117
	v_sub_f32_e32 v146, v126, v118
	v_sub_f32_e32 v147, v127, v119
	ds_read_b128 v[10:13], v5 offset:8304
	ds_read_b128 v[116:119], v5 offset:8320
	ds_read_b128 v[120:123], v4 offset:384
	ds_read_b128 v[124:127], v4 offset:400
	v_pk_mul_f32 v[140:141], v[140:141], v[148:149] op_sel_hi:[1,0]
	v_pk_mul_f32 v[142:143], v[142:143], v[148:149] op_sel_hi:[1,0]
	v_pk_mul_f32 v[144:145], v[144:145], v[148:149] op_sel_hi:[1,0]
	v_pk_mul_f32 v[146:147], v[146:147], v[148:149] op_sel_hi:[1,0]
	v_exp_f32_e32 v140, v140
	v_exp_f32_e32 v141, v141
	v_exp_f32_e32 v142, v142
	v_exp_f32_e32 v143, v143
	v_exp_f32_e32 v144, v144
	v_exp_f32_e32 v145, v145
	v_exp_f32_e32 v146, v146
	v_exp_f32_e32 v147, v147
	s_waitcnt lgkmcnt(5)
	v_lshlrev_b32_e32 v150, 16, v128
	v_and_b32_e32 v151, 0xffff0000, v128
	v_lshlrev_b32_e32 v152, 16, v129
	v_and_b32_e32 v153, 0xffff0000, v129
	v_lshlrev_b32_e32 v154, 16, v130
	v_and_b32_e32 v155, 0xffff0000, v130
	v_lshlrev_b32_e32 v156, 16, v131
	v_and_b32_e32 v157, 0xffff0000, v131
	ds_read_b128 v[128:131], v8 offset:36032
	ds_read_b128 v[136:139], v7 offset:192
	v_pk_mul_f32 v[140:141], v[140:141], v[150:151]
	v_pk_mul_f32 v[142:143], v[142:143], v[152:153]
	v_pk_mul_f32 v[144:145], v[144:145], v[154:155]
	v_pk_mul_f32 v[146:147], v[146:147], v[156:157]
	v_cvt_pk_bf16_f32 v160, v140, v141
	v_cvt_pk_bf16_f32 v161, v142, v143
	v_cvt_pk_bf16_f32 v162, v144, v145
	v_cvt_pk_bf16_f32 v163, v146, v147
	s_waitcnt lgkmcnt(6)
	s_nop 1
	v_mfma_f32_16x16x32_bf16 v[0:3], v[160:163], v[132:135], v[0:3]
	s_waitcnt lgkmcnt(2)
	v_sub_f32_e32 v140, v120, v10
	v_sub_f32_e32 v141, v121, v11
	v_sub_f32_e32 v142, v122, v12
	v_sub_f32_e32 v143, v123, v13
	v_sub_f32_e32 v144, v124, v116
	v_sub_f32_e32 v145, v125, v117
	v_sub_f32_e32 v146, v126, v118
	v_sub_f32_e32 v147, v127, v119
	v_pk_mul_f32 v[140:141], v[140:141], v[148:149] op_sel_hi:[1,0]
	v_pk_mul_f32 v[142:143], v[142:143], v[148:149] op_sel_hi:[1,0]
	v_pk_mul_f32 v[144:145], v[144:145], v[148:149] op_sel_hi:[1,0]
	v_pk_mul_f32 v[146:147], v[146:147], v[148:149] op_sel_hi:[1,0]
	v_exp_f32_e32 v140, v140
	v_exp_f32_e32 v141, v141
	v_exp_f32_e32 v142, v142
	v_exp_f32_e32 v143, v143
	v_exp_f32_e32 v144, v144
	v_exp_f32_e32 v145, v145
	v_exp_f32_e32 v146, v146
	v_exp_f32_e32 v147, v147
	s_waitcnt lgkmcnt(1)
	v_lshlrev_b32_e32 v150, 16, v128
	v_and_b32_e32 v151, 0xffff0000, v128
	v_lshlrev_b32_e32 v152, 16, v129
	v_and_b32_e32 v153, 0xffff0000, v129
	v_lshlrev_b32_e32 v154, 16, v130
	v_and_b32_e32 v155, 0xffff0000, v130
	v_lshlrev_b32_e32 v156, 16, v131
	v_and_b32_e32 v157, 0xffff0000, v131
	v_pk_mul_f32 v[140:141], v[140:141], v[150:151]
	v_pk_mul_f32 v[142:143], v[142:143], v[152:153]
	v_pk_mul_f32 v[144:145], v[144:145], v[154:155]
	v_pk_mul_f32 v[146:147], v[146:147], v[156:157]
	v_cvt_pk_bf16_f32 v160, v140, v141
	v_cvt_pk_bf16_f32 v161, v142, v143
	v_cvt_pk_bf16_f32 v162, v144, v145
	v_cvt_pk_bf16_f32 v163, v146, v147
	s_waitcnt lgkmcnt(0)
	s_nop 1
	v_mfma_f32_16x16x32_bf16 v[0:3], v[160:163], v[136:139], v[0:3]
	s_lshl_b32 s28, s33, 5
	v_or_b32_e32 v4, s37, v88
	s_and_b64 s[36:37], s[48:49], s[12:13]
	v_mul_lo_u32 v4, v4, s29
	v_add3_u32 v4, v89, s28, v4
	s_nop 3
	v_cvt_pk_bf16_f32 v0, v0, s0
	v_cndmask_b32_e64 v0, v0, 0, s[36:37]
	ds_write_b16 v4, v0
	v_cvt_pk_bf16_f32 v0, v1, s0
	s_and_b64 s[36:37], s[48:49], s[14:15]
	v_cndmask_b32_e64 v0, v0, 0, s[36:37]
	ds_write_b16 v4, v0 offset:144
	v_cvt_pk_bf16_f32 v0, v2, s0
	s_and_b64 s[36:37], s[48:49], s[16:17]
	v_cndmask_b32_e64 v0, v0, 0, s[36:37]
	ds_write_b16 v4, v0 offset:288
	v_cvt_pk_bf16_f32 v0, v3, s0
	s_and_b64 s[36:37], s[48:49], s[18:19]
	v_cndmask_b32_e64 v0, v0, 0, s[36:37]
	s_cmp_gt_i32 s21, 1
	ds_write_b16 v4, v0 offset:432
	s_cbranch_scc1 .LBB0_313

	.amdhsa_kernel _Z8yoco_fwd4Args
		.amdhsa_group_segment_fixed_size 21760
		.amdhsa_private_segment_fixed_size 0
		.amdhsa_kernarg_size 680
		.amdhsa_user_sgpr_count 2
		.amdhsa_user_sgpr_dispatch_ptr 0
		.amdhsa_user_sgpr_queue_ptr 0
		.amdhsa_user_sgpr_kernarg_segment_ptr 1
		.amdhsa_user_sgpr_dispatch_id 0
		.amdhsa_user_sgpr_kernarg_preload_length 0
		.amdhsa_user_sgpr_kernarg_preload_offset 0
		.amdhsa_user_sgpr_private_segment_size 0
		.amdhsa_uses_dynamic_stack 0
		.amdhsa_enable_private_segment 0
		.amdhsa_system_sgpr_workgroup_id_x 1
		.amdhsa_system_sgpr_workgroup_id_y 0
		.amdhsa_system_sgpr_workgroup_id_z 0
		.amdhsa_system_sgpr_workgroup_info 0
		.amdhsa_system_vgpr_workitem_id 2
		.amdhsa_next_free_vgpr 256
		.amdhsa_next_free_sgpr 98
		.amdhsa_accum_offset 256
		.amdhsa_reserve_vcc 1
		.amdhsa_float_round_mode_32 0
		.amdhsa_float_round_mode_16_64 0
		.amdhsa_float_denorm_mode_32 3
		.amdhsa_float_denorm_mode_16_64 3
		.amdhsa_dx10_clamp 1
		.amdhsa_ieee_mode 1
		.amdhsa_fp16_overflow 0
		.amdhsa_tg_split 0
		.amdhsa_exception_fp_ieee_invalid_op 0
		.amdhsa_exception_fp_denorm_src 0
		.amdhsa_exception_fp_ieee_div_zero 0
		.amdhsa_exception_fp_ieee_overflow 0
		.amdhsa_exception_fp_ieee_underflow 0
		.amdhsa_exception_fp_ieee_inexact 0
		.amdhsa_exception_int_div_zero 0
	.end_amdhsa_kernel

amdhsa.kernels:
  - .agpr_count:     0
    .args:
      - .offset:         0
        .size:           424
        .value_kind:     by_value
      - .offset:         424
        .size:           4
        .value_kind:     hidden_block_count_x
      - .offset:         428
        .size:           4
        .value_kind:     hidden_block_count_y
      - .offset:         432
        .size:           4
        .value_kind:     hidden_block_count_z
      - .offset:         436
        .size:           2
        .value_kind:     hidden_group_size_x
      - .offset:         438
        .size:           2
        .value_kind:     hidden_group_size_y
      - .offset:         440
        .size:           2
        .value_kind:     hidden_group_size_z
      - .offset:         442
        .size:           2
        .value_kind:     hidden_remainder_x
      - .offset:         444
        .size:           2
        .value_kind:     hidden_remainder_y
      - .offset:         446
        .size:           2
        .value_kind:     hidden_remainder_z
      - .offset:         464
        .size:           8
        .value_kind:     hidden_global_offset_x
      - .offset:         472
        .size:           8
        .value_kind:     hidden_global_offset_y
      - .offset:         480
        .size:           8
        .value_kind:     hidden_global_offset_z
      - .offset:         488
        .size:           2
        .value_kind:     hidden_grid_dims
      - .offset:         512
        .size:           8
        .value_kind:     hidden_multigrid_sync_arg
      - .offset:         544
        .size:           4
        .value_kind:     hidden_dynamic_lds_size
    .group_segment_fixed_size: 21760
    .kernarg_segment_align: 8
    .kernarg_segment_size: 680
    .language:       OpenCL C
    .language_version:
      - 2
      - 0
    .max_flat_workgroup_size: 512
    .name:           _Z8yoco_fwd4Args
    .private_segment_fixed_size: 0
    .sgpr_count:     104
    .sgpr_spill_count: 94
    .symbol:         _Z8yoco_fwd4Args.kd
    .uniform_work_group_size: 1
    .uses_dynamic_stack: false
    .vgpr_count:     256
    .vgpr_spill_count: 0
    .wavefront_size: 64
